# early L1 invalidate in the shadow of the arrival atomic at the P0->P1 and P3->P4 barriers; attention softmax v_pk_mul_f32 split into scalar pairs (section 7.5)
# baseline (speedup 1.0000x reference)
; __device__ __forceinline__ unsigned xb_add(unsigned* p, unsigned v) { return __hip_atomic_fetch_add(p, v, __ATOMIC_RELAXED, __HIP_MEMORY_SCOPE_AGENT); }
; __device__ __forceinline__ void xcd_barrier(const XcdBarrier& b) {
;     ...
;         unsigned nloc = b.st[0], nx = b.st[1];
;         if (nloc == 0u) { xcd_barrier_complete(bar, b.x, nloc, nx); b.st[0] = nloc; b.st[1] = nx; }
;         const unsigned old = xb_add(&bar[XB_XSUB(b.x)], 1u);
.LBB0_50:
	s_mov_b64 s[8:9], exec
	s_lshl_b32 s4, s67, 8
	v_mbcnt_lo_u32_b32 v3, s8, 0
	s_add_u32 s4, s84, s4
	v_mbcnt_hi_u32_b32 v3, s9, v3
	s_addc_u32 s5, s85, 0
	v_cmp_eq_u32_e32 vcc, 0, v3
	s_and_saveexec_b64 s[10:11], vcc
	s_cbranch_execz .LBB0_52
	s_bcnt1_i32_b64 s8, s[8:9]
	v_mov_b32_e32 v5, 0x1000
	v_mov_b32_e32 v6, s8
	global_atomic_add v5, v5, v6, s[4:5] offset:1024 sc0
	buffer_inv sc1

; __device__ __forceinline__ unsigned xb_ld(unsigned* p)              { return __hip_atomic_load(p, __ATOMIC_RELAXED, __HIP_MEMORY_SCOPE_AGENT); }
; #define XB_SPIN(cond, bar) do { unsigned _sp = 0; while (cond) { __builtin_amdgcn_s_sleep(1); \
;     if ((++_sp & 255u) == 0u) { if (xb_ld(&(bar)[XB_TMO])) break; if (_sp > XB_SPIN_CAP) { atomicAdd(&(bar)[XB_TMO], 1u); break; } } } } while (0)
; __device__ __forceinline__ void xcd_barrier(const XcdBarrier& b) {
;     ...
;             XB_SPIN(xb_ld(&bar[XB_XGEN(b.x)]) == gen, bar);
;             __builtin_amdgcn_fence(__ATOMIC_ACQUIRE, "agent");
;             asm volatile("s_waitcnt vmcnt(0)" ::: "memory");
.LBB0_65:
	s_or_b64 exec, exec, s[10:11]
	s_waitcnt vmcnt(0)
	s_waitcnt vmcnt(0)

; __device__ __forceinline__ unsigned xb_ld(unsigned* p)              { return __hip_atomic_load(p, __ATOMIC_RELAXED, __HIP_MEMORY_SCOPE_AGENT); }
; __device__ __forceinline__ unsigned xb_add(unsigned* p, unsigned v) { return __hip_atomic_fetch_add(p, v, __ATOMIC_RELAXED, __HIP_MEMORY_SCOPE_AGENT); }
; #define XB_SPIN(cond, bar) do { unsigned _sp = 0; while (cond) { __builtin_amdgcn_s_sleep(1); \
;     if ((++_sp & 255u) == 0u) { if (xb_ld(&(bar)[XB_TMO])) break; if (_sp > XB_SPIN_CAP) { atomicAdd(&(bar)[XB_TMO], 1u); break; } } } } while (0)
; __device__ __forceinline__ void xcd_barrier(const XcdBarrier& b) {
;     ...
;             else XB_SPIN(xb_ld(&bar[XB_TOPGEN]) == tg, bar);
;             __builtin_amdgcn_fence(__ATOMIC_ACQUIRE, "agent");
;             xb_add(&bar[XB_XGEN(b.x)], 1u);
.LBB0_83:
	s_or_b64 exec, exec, s[8:9]
	s_mov_b64 s[8:9], exec
	v_mbcnt_lo_u32_b32 v2, s8, 0
	v_mbcnt_hi_u32_b32 v2, s9, v2
	v_cmp_eq_u32_e32 vcc, 0, v2
	s_waitcnt vmcnt(0)
	s_and_saveexec_b64 s[10:11], vcc
	s_cbranch_execz .LBB0_85
	s_bcnt1_i32_b64 s8, s[8:9]
	v_mov_b32_e32 v2, 0x2000
	v_mov_b32_e32 v3, s8
	global_atomic_add v2, v3, s[4:5] offset:1024

; __device__ __forceinline__ unsigned pk2(float lo, float hi) { f32x2 v = {lo, hi}; bf16x2_t b = __builtin_convertvector(v, bf16x2_t); return __builtin_bit_cast(unsigned, b); }
; __device__ __forceinline__ void tile_compute(const bf16x8 (&kf)[4], const bf16x8 (&vf)[2][2], const bf16x8 (&qf)[4], unsigned long long w0, unsigned long long w1,
;                                              float shift, f32x16& o0, f32x16& o1, f32x16& zacc, const bf16x8& ones) {
;     ...
;     for (int eg = 0; eg < 2; ++eg) {
;         const unsigned long long w = eg ? w1 : w0;
;         const unsigned wl = (unsigned)w, wh = (unsigned)(w >> 32);
;         float pv[8];
; #pragma unroll
;         for (int p = 0; p < 4; ++p) {
;             pv[p] = (float)((wl >> (8 * p)) & 0xffu) * __builtin_amdgcn_exp2f(st[8 * eg + p]);
;             pv[4 + p] = (float)((wh >> (8 * p)) & 0xffu) * __builtin_amdgcn_exp2f(st[8 * eg + 4 + p]);
;         }
; #pragma unroll
;         for (int p = 0; p < 4; ++p) pw[4 * eg + p] = pk2(pv[2 * p], pv[2 * p + 1]);
;     }
;     const bf16x8 pf0 = __builtin_bit_cast(bf16x8, (u32x4){pw[0], pw[1], pw[2], pw[3]});
;     const bf16x8 pf1 = __builtin_bit_cast(bf16x8, (u32x4){pw[4], pw[5], pw[6], pw[7]});
;     o0 = __builtin_amdgcn_mfma_f32_32x32x16_bf16(vf[0][0], pf0, o0, 0, 0, 0);
;     o1 = __builtin_amdgcn_mfma_f32_32x32x16_bf16(vf[1][0], pf0, o1, 0, 0, 0);
;     zacc = __builtin_amdgcn_mfma_f32_32x32x16_bf16(ones, pf0, zacc, 0, 0, 0);
;     o0 = __builtin_amdgcn_mfma_f32_32x32x16_bf16(vf[0][1], pf1, o0, 0, 0, 0);
;     o1 = __builtin_amdgcn_mfma_f32_32x32x16_bf16(vf[1][1], pf1, o1, 0, 0, 0);
;     zacc = __builtin_amdgcn_mfma_f32_32x32x16_bf16(ones, pf1, zacc, 0, 0, 0);
.LBB0_170:
	s_nop 5
	v_exp_f32_e32 v66, v66
	s_nop 3
	v_exp_f32_e32 v67, v67
	v_exp_f32_e32 v70, v70
	v_exp_f32_e32 v71, v71
	v_exp_f32_e32 v68, v68
	v_exp_f32_e32 v69, v69
	v_cvt_f32_ubyte1_e32 v175, v212
	v_cvt_f32_ubyte0_e32 v174, v212
	v_exp_f32_e32 v72, v72
	v_exp_f32_e32 v73, v73
	v_mul_f32_e32 v66, v66, v174
	v_mul_f32_e32 v67, v67, v175
	v_cvt_f32_ubyte1_e32 v175, v213
	v_cvt_f32_ubyte0_e32 v174, v213
	v_mul_f32_e32 v70, v70, v174
	v_mul_f32_e32 v71, v71, v175
	v_cvt_f32_ubyte3_e32 v175, v212
	v_cvt_f32_ubyte2_e32 v174, v212
	v_mul_f32_e32 v68, v68, v174
	v_mul_f32_e32 v69, v69, v175
	v_cvt_f32_ubyte3_e32 v175, v213
	v_cvt_f32_ubyte2_e32 v174, v213
	v_mul_f32_e32 v72, v72, v174
	v_mul_f32_e32 v73, v73, v175
	v_cvt_pk_bf16_f32 v66, v66, v67
	v_cvt_pk_bf16_f32 v67, v68, v69
	v_cvt_pk_bf16_f32 v68, v70, v71
	v_exp_f32_e32 v70, v74
	v_exp_f32_e32 v71, v75
	v_cvt_pk_bf16_f32 v69, v72, v73
	v_exp_f32_e32 v72, v78
	v_exp_f32_e32 v73, v79
	s_waitcnt vmcnt(4)
	v_mfma_f32_32x32x16_bf16 v[18:33], v[162:165], v[66:69], v[18:33]
	v_cvt_f32_ubyte1_e32 v75, v210
	v_cvt_f32_ubyte0_e32 v74, v210
	v_mul_f32_e64 v70, v70, v74
	v_mul_f32_e64 v71, v71, v75
	v_cvt_f32_ubyte1_e32 v75, v211
	v_cvt_f32_ubyte0_e32 v74, v211
	v_mul_f32_e32 v72, v72, v74
	v_mul_f32_e32 v73, v73, v75
	v_exp_f32_e32 v74, v76
	v_mfma_f32_32x32x16_bf16 v[34:49], v[158:161], v[66:69], v[34:49]
	v_exp_f32_e32 v75, v77
	v_exp_f32_e32 v76, v80
	v_exp_f32_e32 v77, v81
	v_cvt_f32_ubyte3_e32 v79, v210
	v_cvt_f32_ubyte2_e32 v78, v210
	v_mul_f32_e32 v74, v74, v78
	v_mul_f32_e32 v75, v75, v79
	s_cmp_lt_i32 s24, 26
	v_mfma_f32_32x32x16_bf16 v[50:65], v[154:157], v[66:69], v[50:65]
	v_cvt_f32_ubyte3_e32 v67, v211
	v_cvt_f32_ubyte2_e32 v66, v211
	v_mul_f32_e64 v76, v76, v66
	v_mul_f32_e64 v77, v77, v67
	v_cvt_pk_bf16_f32 v66, v70, v71
	v_cvt_pk_bf16_f32 v67, v74, v75
	v_cvt_pk_bf16_f32 v68, v72, v73
	v_cvt_pk_bf16_f32 v69, v76, v77
	s_cselect_b64 s[4:5], -1, 0
	s_cmp_lt_i32 s23, 10
	v_mfma_f32_32x32x16_bf16 v[18:33], v[166:169], v[66:69], v[18:33]
	s_cselect_b64 s[0:1], -1, 0
	s_or_b64 s[4:5], s[4:5], s[0:1]
	s_and_b64 vcc, exec, s[4:5]
	v_mfma_f32_32x32x16_bf16 v[34:49], v[170:173], v[66:69], v[34:49]
	v_mfma_f32_32x32x16_bf16 v[50:65], v[154:157], v[66:69], v[50:65]
	s_cbranch_vccz .LBB0_247

; __device__ __forceinline__ unsigned pk2(float lo, float hi) { f32x2 v = {lo, hi}; bf16x2_t b = __builtin_convertvector(v, bf16x2_t); return __builtin_bit_cast(unsigned, b); }
; __device__ __forceinline__ void tile_compute(const bf16x8 (&kf)[4], const bf16x8 (&vf)[2][2], const bf16x8 (&qf)[4], unsigned long long w0, unsigned long long w1,
;                                              float shift, f32x16& o0, f32x16& o1, f32x16& zacc, const bf16x8& ones) {
;     ...
;     for (int eg = 0; eg < 2; ++eg) {
;         const unsigned long long w = eg ? w1 : w0;
;         const unsigned wl = (unsigned)w, wh = (unsigned)(w >> 32);
;         float pv[8];
; #pragma unroll
;         for (int p = 0; p < 4; ++p) {
;             pv[p] = (float)((wl >> (8 * p)) & 0xffu) * __builtin_amdgcn_exp2f(st[8 * eg + p]);
;             pv[4 + p] = (float)((wh >> (8 * p)) & 0xffu) * __builtin_amdgcn_exp2f(st[8 * eg + 4 + p]);
;         }
; #pragma unroll
;         for (int p = 0; p < 4; ++p) pw[4 * eg + p] = pk2(pv[2 * p], pv[2 * p + 1]);
;     }
;     const bf16x8 pf0 = __builtin_bit_cast(bf16x8, (u32x4){pw[0], pw[1], pw[2], pw[3]});
;     const bf16x8 pf1 = __builtin_bit_cast(bf16x8, (u32x4){pw[4], pw[5], pw[6], pw[7]});
;     o0 = __builtin_amdgcn_mfma_f32_32x32x16_bf16(vf[0][0], pf0, o0, 0, 0, 0);
;     o1 = __builtin_amdgcn_mfma_f32_32x32x16_bf16(vf[1][0], pf0, o1, 0, 0, 0);
;     zacc = __builtin_amdgcn_mfma_f32_32x32x16_bf16(ones, pf0, zacc, 0, 0, 0);
;     o0 = __builtin_amdgcn_mfma_f32_32x32x16_bf16(vf[0][1], pf1, o0, 0, 0, 0);
;     o1 = __builtin_amdgcn_mfma_f32_32x32x16_bf16(vf[1][1], pf1, o1, 0, 0, 0);
;     zacc = __builtin_amdgcn_mfma_f32_32x32x16_bf16(ones, pf1, zacc, 0, 0, 0);
.LBB0_250:
	s_nop 5
	v_exp_f32_e32 v66, v66
	s_nop 3
	v_exp_f32_e32 v67, v67
	v_exp_f32_e32 v70, v70
	v_exp_f32_e32 v71, v71
	v_exp_f32_e32 v68, v68
	v_exp_f32_e32 v69, v69
	v_cvt_f32_ubyte1_e32 v175, v212
	v_cvt_f32_ubyte0_e32 v174, v212
	v_exp_f32_e32 v72, v72
	v_exp_f32_e32 v73, v73
	v_mul_f32_e32 v66, v66, v174
	v_mul_f32_e32 v67, v67, v175
	v_cvt_f32_ubyte1_e32 v175, v213
	v_cvt_f32_ubyte0_e32 v174, v213
	v_mul_f32_e32 v70, v70, v174
	v_mul_f32_e32 v71, v71, v175
	v_cvt_f32_ubyte3_e32 v175, v212
	v_cvt_f32_ubyte2_e32 v174, v212
	v_mul_f32_e32 v68, v68, v174
	v_mul_f32_e32 v69, v69, v175
	v_cvt_f32_ubyte3_e32 v175, v213
	v_cvt_f32_ubyte2_e32 v174, v213
	v_mul_f32_e32 v72, v72, v174
	v_mul_f32_e32 v73, v73, v175
	v_cvt_pk_bf16_f32 v66, v66, v67
	v_cvt_pk_bf16_f32 v67, v68, v69
	v_cvt_pk_bf16_f32 v68, v70, v71
	v_exp_f32_e32 v70, v74
	v_exp_f32_e32 v71, v75
	v_cvt_pk_bf16_f32 v69, v72, v73
	v_exp_f32_e32 v72, v78
	v_exp_f32_e32 v73, v79
	s_waitcnt vmcnt(4)
	v_mfma_f32_32x32x16_bf16 v[18:33], v[162:165], v[66:69], v[18:33]
	v_cvt_f32_ubyte1_e32 v75, v210
	v_cvt_f32_ubyte0_e32 v74, v210
	v_mul_f32_e64 v70, v70, v74
	v_mul_f32_e64 v71, v71, v75
	v_cvt_f32_ubyte1_e32 v75, v211
	v_cvt_f32_ubyte0_e32 v74, v211
	v_mul_f32_e32 v72, v72, v74
	v_mul_f32_e32 v73, v73, v75
	v_exp_f32_e32 v74, v76
	v_mfma_f32_32x32x16_bf16 v[34:49], v[158:161], v[66:69], v[34:49]
	v_exp_f32_e32 v75, v77
	v_exp_f32_e32 v76, v80
	v_exp_f32_e32 v77, v81
	v_cvt_f32_ubyte3_e32 v79, v210
	v_cvt_f32_ubyte2_e32 v78, v210
	v_mul_f32_e32 v74, v74, v78
	v_mul_f32_e32 v75, v75, v79
	s_cmp_lt_i32 s19, 26
	v_mfma_f32_32x32x16_bf16 v[50:65], v[154:157], v[66:69], v[50:65]
	v_cvt_f32_ubyte3_e32 v67, v211
	v_cvt_f32_ubyte2_e32 v66, v211
	v_mul_f32_e64 v76, v76, v66
	v_mul_f32_e64 v77, v77, v67
	v_cvt_pk_bf16_f32 v66, v70, v71
	v_cvt_pk_bf16_f32 v67, v74, v75
	v_cvt_pk_bf16_f32 v68, v72, v73
	v_cvt_pk_bf16_f32 v69, v76, v77
	s_cselect_b64 s[4:5], -1, 0
	s_cmp_lt_i32 s14, 10
	v_mfma_f32_32x32x16_bf16 v[18:33], v[166:169], v[66:69], v[18:33]
	s_cselect_b64 s[0:1], -1, 0
	s_or_b64 s[4:5], s[4:5], s[0:1]
	s_and_b64 vcc, exec, s[4:5]
	v_mfma_f32_32x32x16_bf16 v[34:49], v[170:173], v[66:69], v[34:49]
	v_mfma_f32_32x32x16_bf16 v[50:65], v[154:157], v[66:69], v[50:65]
	s_cbranch_vccz .LBB0_327

; __device__ __forceinline__ unsigned pk2(float lo, float hi) { f32x2 v = {lo, hi}; bf16x2_t b = __builtin_convertvector(v, bf16x2_t); return __builtin_bit_cast(unsigned, b); }
; __device__ __forceinline__ void tile_compute(const bf16x8 (&kf)[4], const bf16x8 (&vf)[2][2], const bf16x8 (&qf)[4], unsigned long long w0, unsigned long long w1,
;                                              float shift, f32x16& o0, f32x16& o1, f32x16& zacc, const bf16x8& ones) {
;     ...
;     for (int eg = 0; eg < 2; ++eg) {
;         const unsigned long long w = eg ? w1 : w0;
;         const unsigned wl = (unsigned)w, wh = (unsigned)(w >> 32);
;         float pv[8];
; #pragma unroll
;         for (int p = 0; p < 4; ++p) {
;             pv[p] = (float)((wl >> (8 * p)) & 0xffu) * __builtin_amdgcn_exp2f(st[8 * eg + p]);
;             pv[4 + p] = (float)((wh >> (8 * p)) & 0xffu) * __builtin_amdgcn_exp2f(st[8 * eg + 4 + p]);
;         }
; #pragma unroll
;         for (int p = 0; p < 4; ++p) pw[4 * eg + p] = pk2(pv[2 * p], pv[2 * p + 1]);
;     }
;     const bf16x8 pf0 = __builtin_bit_cast(bf16x8, (u32x4){pw[0], pw[1], pw[2], pw[3]});
;     const bf16x8 pf1 = __builtin_bit_cast(bf16x8, (u32x4){pw[4], pw[5], pw[6], pw[7]});
;     o0 = __builtin_amdgcn_mfma_f32_32x32x16_bf16(vf[0][0], pf0, o0, 0, 0, 0);
;     o1 = __builtin_amdgcn_mfma_f32_32x32x16_bf16(vf[1][0], pf0, o1, 0, 0, 0);
;     zacc = __builtin_amdgcn_mfma_f32_32x32x16_bf16(ones, pf0, zacc, 0, 0, 0);
;     o0 = __builtin_amdgcn_mfma_f32_32x32x16_bf16(vf[0][1], pf1, o0, 0, 0, 0);
;     o1 = __builtin_amdgcn_mfma_f32_32x32x16_bf16(vf[1][1], pf1, o1, 0, 0, 0);
;     zacc = __builtin_amdgcn_mfma_f32_32x32x16_bf16(ones, pf1, zacc, 0, 0, 0);
.LBB0_334:
	s_nop 5
	v_exp_f32_e32 v66, v66
	s_nop 3
	v_exp_f32_e32 v67, v67
	v_exp_f32_e32 v70, v70
	v_exp_f32_e32 v71, v71
	v_exp_f32_e32 v68, v68
	v_exp_f32_e32 v69, v69
	v_cvt_f32_ubyte1_e32 v175, v212
	v_cvt_f32_ubyte0_e32 v174, v212
	v_exp_f32_e32 v72, v72
	v_exp_f32_e32 v73, v73
	v_mul_f32_e32 v66, v66, v174
	v_mul_f32_e32 v67, v67, v175
	v_cvt_f32_ubyte1_e32 v175, v213
	v_cvt_f32_ubyte0_e32 v174, v213
	v_mul_f32_e32 v70, v70, v174
	v_mul_f32_e32 v71, v71, v175
	v_cvt_f32_ubyte3_e32 v175, v212
	v_cvt_f32_ubyte2_e32 v174, v212
	v_mul_f32_e32 v68, v68, v174
	v_mul_f32_e32 v69, v69, v175
	v_cvt_f32_ubyte3_e32 v175, v213
	v_cvt_f32_ubyte2_e32 v174, v213
	v_mul_f32_e32 v72, v72, v174
	v_mul_f32_e32 v73, v73, v175
	v_cvt_pk_bf16_f32 v66, v66, v67
	v_cvt_pk_bf16_f32 v67, v68, v69
	v_cvt_pk_bf16_f32 v68, v70, v71
	v_exp_f32_e32 v70, v74
	v_exp_f32_e32 v71, v75
	v_cvt_pk_bf16_f32 v69, v72, v73
	v_exp_f32_e32 v72, v78
	v_exp_f32_e32 v73, v79
	v_mfma_f32_32x32x16_bf16 v[18:33], v[162:165], v[66:69], v[18:33]
	v_cvt_f32_ubyte1_e32 v75, v210
	v_cvt_f32_ubyte0_e32 v74, v210
	v_mul_f32_e64 v70, v70, v74
	v_mul_f32_e64 v71, v71, v75
	v_cvt_f32_ubyte1_e32 v75, v211
	v_cvt_f32_ubyte0_e32 v74, v211
	v_mul_f32_e32 v72, v72, v74
	v_mul_f32_e32 v73, v73, v75
	v_exp_f32_e32 v74, v76
	v_mfma_f32_32x32x16_bf16 v[34:49], v[158:161], v[66:69], v[34:49]
	v_exp_f32_e32 v75, v77
	v_exp_f32_e32 v76, v80
	v_exp_f32_e32 v77, v81
	v_cvt_f32_ubyte3_e32 v79, v210
	v_cvt_f32_ubyte2_e32 v78, v210
	v_mul_f32_e32 v74, v74, v78
	v_mul_f32_e32 v75, v75, v79
	s_cmp_lt_i32 s66, 26
	v_mfma_f32_32x32x16_bf16 v[50:65], v[154:157], v[66:69], v[50:65]
	v_cvt_f32_ubyte3_e32 v67, v211
	v_cvt_f32_ubyte2_e32 v66, v211
	v_mul_f32_e64 v76, v76, v66
	v_mul_f32_e64 v77, v77, v67
	v_cvt_pk_bf16_f32 v66, v70, v71
	v_cvt_pk_bf16_f32 v67, v74, v75
	v_cvt_pk_bf16_f32 v68, v72, v73
	v_cvt_pk_bf16_f32 v69, v76, v77
	s_cselect_b64 s[4:5], -1, 0
	s_cmp_lt_i32 s72, 10
	v_mfma_f32_32x32x16_bf16 v[18:33], v[166:169], v[66:69], v[18:33]
	s_cselect_b64 s[0:1], -1, 0
	s_or_b64 s[4:5], s[4:5], s[0:1]
	s_and_b64 vcc, exec, s[4:5]
	v_mfma_f32_32x32x16_bf16 v[34:49], v[170:173], v[66:69], v[34:49]
	v_mfma_f32_32x32x16_bf16 v[50:65], v[154:157], v[66:69], v[50:65]
	s_cbranch_vccz .LBB0_430

; __device__ __forceinline__ unsigned pk2(float lo, float hi) { f32x2 v = {lo, hi}; bf16x2_t b = __builtin_convertvector(v, bf16x2_t); return __builtin_bit_cast(unsigned, b); }
; __device__ __forceinline__ void tile_compute(const bf16x8 (&kf)[4], const bf16x8 (&vf)[2][2], const bf16x8 (&qf)[4], unsigned long long w0, unsigned long long w1,
;                                              float shift, f32x16& o0, f32x16& o1, f32x16& zacc, const bf16x8& ones) {
;     ...
;     for (int eg = 0; eg < 2; ++eg) {
;         const unsigned long long w = eg ? w1 : w0;
;         const unsigned wl = (unsigned)w, wh = (unsigned)(w >> 32);
;         float pv[8];
; #pragma unroll
;         for (int p = 0; p < 4; ++p) {
;             pv[p] = (float)((wl >> (8 * p)) & 0xffu) * __builtin_amdgcn_exp2f(st[8 * eg + p]);
;             pv[4 + p] = (float)((wh >> (8 * p)) & 0xffu) * __builtin_amdgcn_exp2f(st[8 * eg + 4 + p]);
;         }
; #pragma unroll
;         for (int p = 0; p < 4; ++p) pw[4 * eg + p] = pk2(pv[2 * p], pv[2 * p + 1]);
;     }
;     const bf16x8 pf0 = __builtin_bit_cast(bf16x8, (u32x4){pw[0], pw[1], pw[2], pw[3]});
;     const bf16x8 pf1 = __builtin_bit_cast(bf16x8, (u32x4){pw[4], pw[5], pw[6], pw[7]});
;     o0 = __builtin_amdgcn_mfma_f32_32x32x16_bf16(vf[0][0], pf0, o0, 0, 0, 0);
;     o1 = __builtin_amdgcn_mfma_f32_32x32x16_bf16(vf[1][0], pf0, o1, 0, 0, 0);
;     zacc = __builtin_amdgcn_mfma_f32_32x32x16_bf16(ones, pf0, zacc, 0, 0, 0);
;     o0 = __builtin_amdgcn_mfma_f32_32x32x16_bf16(vf[0][1], pf1, o0, 0, 0, 0);
;     o1 = __builtin_amdgcn_mfma_f32_32x32x16_bf16(vf[1][1], pf1, o1, 0, 0, 0);
;     zacc = __builtin_amdgcn_mfma_f32_32x32x16_bf16(ones, pf1, zacc, 0, 0, 0);
.LBB0_437:
	s_nop 5
	v_exp_f32_e32 v66, v66
	s_nop 3
	v_exp_f32_e32 v67, v67
	v_exp_f32_e32 v70, v70
	v_exp_f32_e32 v71, v71
	v_exp_f32_e32 v68, v68
	v_exp_f32_e32 v69, v69
	v_cvt_f32_ubyte1_e32 v175, v212
	v_cvt_f32_ubyte0_e32 v174, v212
	v_exp_f32_e32 v72, v72
	v_exp_f32_e32 v73, v73
	v_mul_f32_e32 v66, v66, v174
	v_mul_f32_e32 v67, v67, v175
	v_cvt_f32_ubyte1_e32 v175, v213
	v_cvt_f32_ubyte0_e32 v174, v213
	v_mul_f32_e32 v70, v70, v174
	v_mul_f32_e32 v71, v71, v175
	v_cvt_f32_ubyte3_e32 v175, v212
	v_cvt_f32_ubyte2_e32 v174, v212
	v_mul_f32_e32 v68, v68, v174
	v_mul_f32_e32 v69, v69, v175
	v_cvt_f32_ubyte3_e32 v175, v213
	v_cvt_f32_ubyte2_e32 v174, v213
	v_mul_f32_e32 v72, v72, v174
	v_mul_f32_e32 v73, v73, v175
	v_cvt_pk_bf16_f32 v66, v66, v67
	v_cvt_pk_bf16_f32 v67, v68, v69
	v_cvt_pk_bf16_f32 v68, v70, v71
	v_exp_f32_e32 v70, v74
	v_exp_f32_e32 v71, v75
	v_cvt_pk_bf16_f32 v69, v72, v73
	v_exp_f32_e32 v72, v78
	v_exp_f32_e32 v73, v79
	v_mfma_f32_32x32x16_bf16 v[18:33], v[162:165], v[66:69], v[18:33]
	v_cvt_f32_ubyte1_e32 v75, v210
	v_cvt_f32_ubyte0_e32 v74, v210
	v_mul_f32_e64 v70, v70, v74
	v_mul_f32_e64 v71, v71, v75
	v_cvt_f32_ubyte1_e32 v75, v211
	v_cvt_f32_ubyte0_e32 v74, v211
	v_mul_f32_e32 v72, v72, v74
	v_mul_f32_e32 v73, v73, v75
	v_exp_f32_e32 v74, v76
	v_mfma_f32_32x32x16_bf16 v[34:49], v[158:161], v[66:69], v[34:49]
	v_exp_f32_e32 v75, v77
	v_exp_f32_e32 v76, v80
	v_exp_f32_e32 v77, v81
	v_cvt_f32_ubyte3_e32 v79, v210
	v_cvt_f32_ubyte2_e32 v78, v210
	v_mul_f32_e32 v74, v74, v78
	v_mul_f32_e32 v75, v75, v79
	s_cmp_lt_i32 s56, 26
	v_mfma_f32_32x32x16_bf16 v[50:65], v[154:157], v[66:69], v[50:65]
	v_cvt_f32_ubyte3_e32 v67, v211
	v_cvt_f32_ubyte2_e32 v66, v211
	v_mul_f32_e64 v76, v76, v66
	v_mul_f32_e64 v77, v77, v67
	v_cvt_pk_bf16_f32 v66, v70, v71
	v_cvt_pk_bf16_f32 v67, v74, v75
	v_cvt_pk_bf16_f32 v68, v72, v73
	v_cvt_pk_bf16_f32 v69, v76, v77
	s_cselect_b64 s[4:5], -1, 0
	s_cmp_lt_i32 s24, 10
	v_mfma_f32_32x32x16_bf16 v[18:33], v[166:169], v[66:69], v[18:33]
	s_cselect_b64 s[0:1], -1, 0
	s_or_b64 s[4:5], s[4:5], s[0:1]
	s_and_b64 vcc, exec, s[4:5]
	v_mfma_f32_32x32x16_bf16 v[34:49], v[170:173], v[66:69], v[34:49]
	v_mfma_f32_32x32x16_bf16 v[50:65], v[154:157], v[66:69], v[50:65]
	s_cbranch_vccz .LBB0_533

; __device__ __forceinline__ unsigned xb_ld(unsigned* p)              { return __hip_atomic_load(p, __ATOMIC_RELAXED, __HIP_MEMORY_SCOPE_AGENT); }
; __device__ __forceinline__ unsigned xb_add(unsigned* p, unsigned v) { return __hip_atomic_fetch_add(p, v, __ATOMIC_RELAXED, __HIP_MEMORY_SCOPE_AGENT); }
; #define XB_SPIN(cond, bar) do { unsigned _sp = 0; while (cond) { __builtin_amdgcn_s_sleep(1); \
;     if ((++_sp & 255u) == 0u) { if (xb_ld(&(bar)[XB_TMO])) break; if (_sp > XB_SPIN_CAP) { atomicAdd(&(bar)[XB_TMO], 1u); break; } } } } while (0)
; __device__ __forceinline__ void xcd_barrier(const XcdBarrier& b) {
;     ...
;         unsigned nloc = b.st[0], nx = b.st[1];
;         if (nloc == 0u) { xcd_barrier_complete(bar, b.x, nloc, nx); b.st[0] = nloc; b.st[1] = nx; }
;         const unsigned old = xb_add(&bar[XB_XSUB(b.x)], 1u);
;         const unsigned gen = old / nloc;
;         if (old + 1u == (gen + 1u) * nloc) {
;             __builtin_amdgcn_fence(__ATOMIC_RELEASE, "agent");
;             asm volatile("s_waitcnt vmcnt(0)" ::: "memory");
;             const unsigned og = xb_add(&bar[XB_TOP], 1u);
;             const unsigned tg = og / nx;
;             if (og + 1u == (tg + 1u) * nx) xb_add(&bar[XB_TOPGEN], 1u);
;             else XB_SPIN(xb_ld(&bar[XB_TOPGEN]) == tg, bar);
;             __builtin_amdgcn_fence(__ATOMIC_ACQUIRE, "agent");
;             xb_add(&bar[XB_XGEN(b.x)], 1u);
;             asm volatile("s_waitcnt vmcnt(0)" ::: "memory");
;         } else {
;             XB_SPIN(xb_ld(&bar[XB_XGEN(b.x)]) == gen, bar);
.LBB0_659:
	s_mov_b64 s[8:9], exec
	s_lshl_b32 s4, s67, 8
	v_mbcnt_lo_u32_b32 v2, s8, 0
	s_add_u32 s6, s84, s4
	v_mbcnt_hi_u32_b32 v2, s9, v2
	s_mov_b32 s5, 0
	s_addc_u32 s7, s85, 0
	v_cmp_eq_u32_e32 vcc, 0, v2
	s_and_saveexec_b64 s[10:11], vcc
	s_cbranch_execz .LBB0_661
	s_bcnt1_i32_b64 s4, s[8:9]
	v_mov_b32_e32 v4, 0x1000
	v_mov_b32_e32 v5, s4
	global_atomic_add v4, v4, v5, s[6:7] offset:1024 sc0
	s_cmp_eq_u32 s32, 0
	s_cbranch_scc0 .Lxb3_noearly
	buffer_inv sc1
.Lxb3_noearly:
.LBB0_661:
	s_or_b64 exec, exec, s[10:11]
	v_cvt_f32_u32_e32 v5, v3
	s_waitcnt vmcnt(0)
	v_readfirstlane_b32 s8, v4
	v_sub_u32_e32 v4, 0, v3
	s_lshl_b32 s4, s67, 6
	v_rcp_iflag_f32_e32 v5, v5
	v_add_u32_e32 v6, s8, v2
	v_mul_f32_e32 v5, 0x4f7ffffe, v5
	v_cvt_u32_f32_e32 v5, v5
	v_mul_lo_u32 v2, v4, v5
	v_mul_hi_u32 v2, v5, v2
	v_add_u32_e32 v2, v5, v2
	v_mul_hi_u32 v2, v6, v2
	v_mul_lo_u32 v4, v2, v3
	v_sub_u32_e32 v4, v6, v4
	v_add_u32_e32 v5, 1, v2
	v_cmp_ge_u32_e32 vcc, v4, v3
	s_nop 1
	v_cndmask_b32_e32 v2, v2, v5, vcc
	v_sub_u32_e32 v5, v4, v3
	v_cndmask_b32_e32 v4, v4, v5, vcc
	v_add_u32_e32 v5, 1, v2
	v_cmp_ge_u32_e32 vcc, v4, v3
	v_add_u32_e32 v4, 1, v6
	s_nop 0
	v_cndmask_b32_e32 v2, v2, v5, vcc
	v_mul_lo_u32 v5, v3, v2
	v_add_u32_e32 v3, v5, v3
	v_cmp_ne_u32_e32 vcc, v4, v3
	s_and_saveexec_b64 s[8:9], vcc
	s_xor_b64 s[8:9], exec, s[8:9]
	s_cbranch_execz .LBB0_675
	s_waitcnt lgkmcnt(0)
	v_mov_b32_e32 v1, 0x2000
	global_load_dword v1, v1, s[6:7] offset:1024 sc1
	s_add_u32 s12, s6, 0x2400
	s_addc_u32 s13, s7, 0
	s_waitcnt vmcnt(0)
	v_cmp_eq_u32_e32 vcc, v1, v2
	s_and_saveexec_b64 s[10:11], vcc
	s_cbranch_execz .LBB0_674
	s_mov_b32 s24, 1
	s_mov_b64 s[14:15], 0
	v_mov_b32_e32 v1, 0
	s_branch .LBB0_665

; __device__ __forceinline__ unsigned xb_ld(unsigned* p)              { return __hip_atomic_load(p, __ATOMIC_RELAXED, __HIP_MEMORY_SCOPE_AGENT); }
; __device__ __forceinline__ unsigned xb_add(unsigned* p, unsigned v) { return __hip_atomic_fetch_add(p, v, __ATOMIC_RELAXED, __HIP_MEMORY_SCOPE_AGENT); }
; #define XB_SPIN(cond, bar) do { unsigned _sp = 0; while (cond) { __builtin_amdgcn_s_sleep(1); \
;     if ((++_sp & 255u) == 0u) { if (xb_ld(&(bar)[XB_TMO])) break; if (_sp > XB_SPIN_CAP) { atomicAdd(&(bar)[XB_TMO], 1u); break; } } } } while (0)
; __device__ __forceinline__ void xcd_barrier(const XcdBarrier& b) {
;     ...
;         if (old + 1u == (gen + 1u) * nloc) {
;             __builtin_amdgcn_fence(__ATOMIC_RELEASE, "agent");
;             asm volatile("s_waitcnt vmcnt(0)" ::: "memory");
;             const unsigned og = xb_add(&bar[XB_TOP], 1u);
;             const unsigned tg = og / nx;
;             if (og + 1u == (tg + 1u) * nx) xb_add(&bar[XB_TOPGEN], 1u);
;             else XB_SPIN(xb_ld(&bar[XB_TOPGEN]) == tg, bar);
;             __builtin_amdgcn_fence(__ATOMIC_ACQUIRE, "agent");
;             xb_add(&bar[XB_XGEN(b.x)], 1u);
;             asm volatile("s_waitcnt vmcnt(0)" ::: "memory");
;         } else {
;             XB_SPIN(xb_ld(&bar[XB_XGEN(b.x)]) == gen, bar);
;             __builtin_amdgcn_fence(__ATOMIC_ACQUIRE, "agent");
;             asm volatile("s_waitcnt vmcnt(0)" ::: "memory");
.LBB0_674:
	s_or_b64 exec, exec, s[10:11]
	s_waitcnt vmcnt(0)
	s_cmp_eq_u32 s32, 0
	s_cbranch_scc1 .Lxb3_i0
	buffer_inv sc1
.Lxb3_i0:
	s_waitcnt vmcnt(0)
.LBB0_675:
	s_andn2_saveexec_b64 s[8:9], s[8:9]
	s_cbranch_execz .LBB0_695
	s_mov_b64 s[10:11], exec
	s_cmp_eq_u32 s32, 0
	s_cbranch_scc1 .Lxb3_rel
	buffer_wbl2 sc1
	s_waitcnt lgkmcnt(0)
	s_waitcnt vmcnt(0)
	v_mbcnt_lo_u32_b32 v2, s10, 0
	v_mbcnt_hi_u32_b32 v2, s11, v2
	v_cmp_eq_u32_e32 vcc, 0, v2
	s_and_saveexec_b64 s[12:13], vcc
	s_cbranch_execz .LBB0_678
	s_bcnt1_i32_b64 s10, s[10:11]
	v_mov_b32_e32 v3, 0x3000
	v_mov_b32_e32 v4, s10
	global_atomic_add v3, v3, v4, s[84:85] offset:1024 sc0

; __device__ __forceinline__ unsigned xb_add(unsigned* p, unsigned v) { return __hip_atomic_fetch_add(p, v, __ATOMIC_RELAXED, __HIP_MEMORY_SCOPE_AGENT); }
; __device__ __forceinline__ void xcd_barrier(const XcdBarrier& b) {
;     ...
;             __builtin_amdgcn_fence(__ATOMIC_ACQUIRE, "agent");
;             xb_add(&bar[XB_XGEN(b.x)], 1u);
;             asm volatile("s_waitcnt vmcnt(0)" ::: "memory");
.Lxb3_rel:
.LBB0_692:
	s_or_b64 exec, exec, s[10:11]
	s_mov_b64 s[10:11], exec
	v_mbcnt_lo_u32_b32 v1, s10, 0
	v_mbcnt_hi_u32_b32 v1, s11, v1
	v_cmp_eq_u32_e32 vcc, 0, v1
	s_waitcnt vmcnt(0)
	s_cmp_eq_u32 s32, 0
	s_cbranch_scc1 .Lxb3_i1
	buffer_inv sc1
.Lxb3_i1:
	s_and_saveexec_b64 s[12:13], vcc
	s_cbranch_execz .LBB0_694
	s_bcnt1_i32_b64 s10, s[10:11]
	v_mov_b32_e32 v1, 0x2000
	v_mov_b32_e32 v2, s10
	global_atomic_add v1, v2, s[6:7] offset:1024
